# stack4 + GEMM1 K-loop: one static s_setprio 1 for waves 4-7 before the loop, the 16 per-segment priority flips deleted
# baseline (speedup 1.0000x reference)
; #define PG8_SCHED __builtin_amdgcn_sched_barrier(0)
; template <class Epi, class Sched, bool ALIGN_EPI = false, bool SP2 = false>
; __device__ __forceinline__ void gemm_phase(PG8_LAS unsigned char* lds, const Gemm g, const Sched& S, const Epi& E) {
;     ...
;         for (int t = 0; t < nt; t += 2) {
;             if constexpr (Epi::HOOK) { if (t == 4 || t == 12) { PG8_SCHED; E.hook(acc, cur, t == 4 ? 0 : 1, wr, wc, fr, fq); asm volatile("" ::: "memory"); PG8_SCHED; } }
;             const bool last = (t == nt - 2);
.LBB0_398:
	v_readfirstlane_b32 s98, v212
	s_nop 3
	s_lshr_b32 s98, s98, 6
	s_cmp_ge_u32 s98, 4
	s_cbranch_scc0 .Lprio_done
	s_setprio 1

; #define PG8_STAGE(bufoff, gbase, voff) do { _Pragma("unroll") for (int _i = 0; _i < 2; ++_i) \
;         __builtin_amdgcn_global_load_lds((const unsigned*)((const char*)(gbase) + (voff)[_i]), (PG8_LAS unsigned*)(lds + (bufoff) + ldsw + _i * 8192), 16, 0, 0); } while (0)
; #define PG8_LDA(dst, b, h) do { _Pragma("unroll") for (int m = 0; m < 4; ++m) _Pragma("unroll") for (int k = 0; k < 2; ++k) dst[m][k] = *(const PG8_LAS bf16x8*)(lds + PG8_SA(b, h) + aoff + m * 2048 + k * 1024); } while (0)
; #define PG8_LDB(dst, b, h) do { _Pragma("unroll") for (int n = 0; n < 2; ++n) _Pragma("unroll") for (int k = 0; k < 2; ++k) dst[n][k] = *(const PG8_LAS bf16x8*)(lds + PG8_SB(b, h) + boff + n * 2048 + k * 1024); } while (0)
; #define PG8_MMA(ai, bj, At, Bt) do { __builtin_amdgcn_s_setprio(1); _Pragma("unroll") for (int m = 0; m < 4; ++m) _Pragma("unroll") for (int n = 0; n < 2; ++n) _Pragma("unroll") for (int k = 0; k < 2; ++k) \
;         acc[ai][bj][m][n] = __builtin_amdgcn_mfma_f32_16x16x32_bf16(Bt[n][k], At[m][k], acc[ai][bj][m][n], 0, 0, 0); __builtin_amdgcn_s_setprio(0); } while (0)
; #define PG8_WAIT_V(n) asm volatile("s_waitcnt vmcnt(" #n ")" ::: "memory")
; #define PG8_WAIT_L(n) asm volatile("s_waitcnt lgkmcnt(" #n ")" ::: "memory")
; #define PG8_BAR __builtin_amdgcn_s_barrier()
; #define PG8_SCHED __builtin_amdgcn_sched_barrier(0)
; template <class Epi, class Sched, bool ALIGN_EPI = false, bool SP2 = false>
; __device__ __forceinline__ void gemm_phase(PG8_LAS unsigned char* lds, const Gemm g, const Sched& S, const Epi& E) {
;     ...
;             PG8_LDB(B0, 0, 0); PG8_LDB(B1, 0, 1); PG8_SCHED; PG8_LDA(At, 0, 0); PG8_STAGE(PG8_SA(1, 1), a1 + hstep, voffA);
;             PG8_WAIT_V(8); PG8_WAIT_L(0); PG8_BAR; PG8_MMA(0, 0, At, B0); PG8_MMA(0, 1, At, B1); PG8_BAR; PG8_SCHED;
;             PG8_LDA(At, 0, 1); PG8_STAGE(PG8_SB(0, 0), b2, voffB); PG8_STAGE(PG8_SB(0, 1), b2 + hstep, voffB); PG8_STAGE(PG8_SA(0, 0), a2, voffA);
;             PG8_WAIT_V(8); PG8_WAIT_L(0); PG8_BAR; PG8_MMA(1, 0, At, B0); PG8_MMA(1, 1, At, B1); PG8_BAR; PG8_SCHED;
.LBB0_399:
	v_or_b32_e32 v142, 0x10000, v141
	v_add_u32_e32 v146, 0x10400, v141
	v_add_u32_e32 v150, 0x10800, v141
	v_add_u32_e32 v154, 0x10c00, v141
	v_or_b32_e32 v158, 0x14000, v141
	v_add_u32_e32 v162, 0x14400, v141
	v_add_u32_e32 v166, 0x14800, v141
	v_add_u32_e32 v170, 0x14c00, v141
	s_add_i32 s74, s62, 2
	ds_read_b128 v[142:145], v142
	ds_read_b128 v[146:149], v146
	ds_read_b128 v[150:153], v150
	ds_read_b128 v[154:157], v154
	ds_read_b128 v[158:161], v158
	ds_read_b128 v[162:165], v162
	ds_read_b128 v[166:169], v166
	ds_read_b128 v[170:173], v170
	s_add_u32 s75, s60, 0x80
	s_addc_u32 s63, s61, 0
	s_cmp_eq_u32 s68, s62
	s_cselect_b32 s62, s40, s75
	s_cselect_b32 s63, s41, s63
	s_cselect_b32 s77, s53, s73
	s_cselect_b32 s76, s52, s55
	s_add_i32 m0, s12, 0xc000
	ds_read_b128 v[174:177], v140
	ds_read_b128 v[178:181], v140 offset:1024
	ds_read_b128 v[182:185], v140 offset:2048
	ds_read_b128 v[186:189], v140 offset:3072
	ds_read_b128 v[190:193], v140 offset:4096
	ds_read_b128 v[202:205], v140 offset:5120
	ds_read_b128 v[206:209], v140 offset:6144
	ds_read_b128 v[230:233], v140 offset:7168
	global_load_lds_dwordx4 v136, s[60:61]
	s_add_i32 m0, s12, 0xe000
	s_nop 0
	global_load_lds_dwordx4 v138, s[60:61]
	s_waitcnt vmcnt(8)
	s_waitcnt lgkmcnt(0)
	s_barrier
	s_waitcnt lgkmcnt(0)
	v_mfma_f32_16x16x32_bf16 v[126:129], v[142:145], v[174:177], v[126:129]
	v_mfma_f32_16x16x32_bf16 v[122:125], v[150:153], v[174:177], v[122:125]
	v_mfma_f32_16x16x32_bf16 v[118:121], v[142:145], v[182:185], v[118:121]
	v_mfma_f32_16x16x32_bf16 v[114:117], v[150:153], v[182:185], v[114:117]
	v_mfma_f32_16x16x32_bf16 v[110:113], v[142:145], v[190:193], v[110:113]
	v_mfma_f32_16x16x32_bf16 v[106:109], v[150:153], v[190:193], v[106:109]
	v_mfma_f32_16x16x32_bf16 v[102:105], v[142:145], v[206:209], v[102:105]
	v_mfma_f32_16x16x32_bf16 v[98:101], v[150:153], v[206:209], v[98:101]
	v_mfma_f32_16x16x32_bf16 v[126:129], v[146:149], v[178:181], v[126:129]
	v_mfma_f32_16x16x32_bf16 v[122:125], v[154:157], v[178:181], v[122:125]
	v_mfma_f32_16x16x32_bf16 v[118:121], v[146:149], v[186:189], v[118:121]
	v_mfma_f32_16x16x32_bf16 v[114:117], v[154:157], v[186:189], v[114:117]
	v_mfma_f32_16x16x32_bf16 v[110:113], v[146:149], v[202:205], v[110:113]
	v_mfma_f32_16x16x32_bf16 v[106:109], v[154:157], v[202:205], v[106:109]
	v_mfma_f32_16x16x32_bf16 v[102:105], v[146:149], v[230:233], v[102:105]
	v_mfma_f32_16x16x32_bf16 v[98:101], v[154:157], v[230:233], v[98:101]
	v_mfma_f32_16x16x32_bf16 v[68:71], v[158:161], v[174:177], v[68:71]
	v_mfma_f32_16x16x32_bf16 v[64:67], v[166:169], v[174:177], v[64:67]
	v_mfma_f32_16x16x32_bf16 v[60:63], v[158:161], v[182:185], v[60:63]
	v_mfma_f32_16x16x32_bf16 v[56:59], v[166:169], v[182:185], v[56:59]
	v_mfma_f32_16x16x32_bf16 v[52:55], v[158:161], v[190:193], v[52:55]
	v_mfma_f32_16x16x32_bf16 v[48:51], v[166:169], v[190:193], v[48:51]
	v_mfma_f32_16x16x32_bf16 v[44:47], v[158:161], v[206:209], v[44:47]
	v_mfma_f32_16x16x32_bf16 v[40:43], v[166:169], v[206:209], v[40:43]
	v_mfma_f32_16x16x32_bf16 v[68:71], v[162:165], v[178:181], v[68:71]
	v_mfma_f32_16x16x32_bf16 v[64:67], v[170:173], v[178:181], v[64:67]
	v_mfma_f32_16x16x32_bf16 v[60:63], v[162:165], v[186:189], v[60:63]
	v_mfma_f32_16x16x32_bf16 v[56:59], v[170:173], v[186:189], v[56:59]
	v_mfma_f32_16x16x32_bf16 v[52:55], v[162:165], v[202:205], v[52:55]
	v_mfma_f32_16x16x32_bf16 v[48:51], v[170:173], v[202:205], v[48:51]
	v_mfma_f32_16x16x32_bf16 v[44:47], v[162:165], v[230:233], v[44:47]
	v_mfma_f32_16x16x32_bf16 v[40:43], v[170:173], v[230:233], v[40:43]
	s_barrier
	s_mov_b32 m0, s13
	ds_read_b128 v[174:177], v140 offset:16384
	ds_read_b128 v[178:181], v140 offset:17408
	ds_read_b128 v[182:185], v140 offset:18432
	ds_read_b128 v[186:189], v140 offset:19456
	ds_read_b128 v[190:193], v140 offset:20480
	ds_read_b128 v[202:205], v140 offset:21504
	ds_read_b128 v[206:209], v140 offset:22528
	ds_read_b128 v[230:233], v140 offset:23552
	global_load_lds_dwordx4 v96, s[76:77]
	s_mov_b32 m0, s16
	s_nop 0
	global_load_lds_dwordx4 v130, s[76:77]
	s_add_u32 s98, s76, s8
	s_addc_u32 s99, s77, s9
	s_add_u32 s76, s76, s42
	s_addc_u32 s77, s77, s43
	s_add_u32 s100, s76, s8
	s_addc_u32 s101, s77, s9
	s_mov_b32 m0, s17
	s_nop 0
	global_load_lds_dwordx4 v96, s[76:77]
	s_mov_b32 m0, s20
	s_nop 0
	global_load_lds_dwordx4 v130, s[76:77]
	s_mov_b32 m0, s12
	s_nop 0
	global_load_lds_dwordx4 v134, s[62:63]
	s_mov_b32 m0, s21
	s_nop 0
	global_load_lds_dwordx4 v132, s[62:63]
	s_waitcnt vmcnt(8)
	s_waitcnt lgkmcnt(0)
	s_barrier
; #define PG8_STAGE(bufoff, gbase, voff) do { _Pragma("unroll") for (int _i = 0; _i < 2; ++_i) \
;         __builtin_amdgcn_global_load_lds((const unsigned*)((const char*)(gbase) + (voff)[_i]), (PG8_LAS unsigned*)(lds + (bufoff) + ldsw + _i * 8192), 16, 0, 0); } while (0)
; #define PG8_LDA(dst, b, h) do { _Pragma("unroll") for (int m = 0; m < 4; ++m) _Pragma("unroll") for (int k = 0; k < 2; ++k) dst[m][k] = *(const PG8_LAS bf16x8*)(lds + PG8_SA(b, h) + aoff + m * 2048 + k * 1024); } while (0)
; #define PG8_LDB(dst, b, h) do { _Pragma("unroll") for (int n = 0; n < 2; ++n) _Pragma("unroll") for (int k = 0; k < 2; ++k) dst[n][k] = *(const PG8_LAS bf16x8*)(lds + PG8_SB(b, h) + boff + n * 2048 + k * 1024); } while (0)
; #define PG8_MMA(ai, bj, At, Bt) do { __builtin_amdgcn_s_setprio(1); _Pragma("unroll") for (int m = 0; m < 4; ++m) _Pragma("unroll") for (int n = 0; n < 2; ++n) _Pragma("unroll") for (int k = 0; k < 2; ++k) \
;         acc[ai][bj][m][n] = __builtin_amdgcn_mfma_f32_16x16x32_bf16(Bt[n][k], At[m][k], acc[ai][bj][m][n], 0, 0, 0); __builtin_amdgcn_s_setprio(0); } while (0)
; #define PG8_WAIT_V(n) asm volatile("s_waitcnt vmcnt(" #n ")" ::: "memory")
; #define PG8_WAIT_L(n) asm volatile("s_waitcnt lgkmcnt(" #n ")" ::: "memory")
; #define PG8_BAR __builtin_amdgcn_s_barrier()
; #define PG8_SCHED __builtin_amdgcn_sched_barrier(0)
; template <class Epi, class Sched, bool ALIGN_EPI = false, bool SP2 = false>
; __device__ __forceinline__ void gemm_phase(PG8_LAS unsigned char* lds, const Gemm g, const Sched& S, const Epi& E) {
;     ...
;             PG8_WAIT_V(8); PG8_WAIT_L(0); PG8_BAR; PG8_MMA(1, 0, At, B0); PG8_MMA(1, 1, At, B1); PG8_BAR; PG8_SCHED;
;             PG8_LDB(B0, 1, 0); PG8_LDB(B1, 1, 1); PG8_SCHED; PG8_LDA(At, 1, 0); PG8_STAGE(PG8_SA(0, 1), a2 + hstep, voffA);
;             PG8_WAIT_V(8); PG8_WAIT_L(0); PG8_BAR; PG8_MMA(0, 0, At, B0); PG8_MMA(0, 1, At, B1); PG8_BAR; PG8_SCHED;
	s_waitcnt lgkmcnt(0)
	v_mfma_f32_16x16x32_bf16 v[92:95], v[142:145], v[174:177], v[92:95]
	v_mfma_f32_16x16x32_bf16 v[88:91], v[150:153], v[174:177], v[88:91]
	v_mfma_f32_16x16x32_bf16 v[84:87], v[142:145], v[182:185], v[84:87]
	v_mfma_f32_16x16x32_bf16 v[80:83], v[150:153], v[182:185], v[80:83]
	v_mfma_f32_16x16x32_bf16 v[76:79], v[142:145], v[190:193], v[76:79]
	v_mfma_f32_16x16x32_bf16 v[72:75], v[150:153], v[190:193], v[72:75]
	v_mfma_f32_16x16x32_bf16 v[12:15], v[142:145], v[206:209], v[12:15]
	v_mfma_f32_16x16x32_bf16 v[8:11], v[150:153], v[206:209], v[8:11]
	v_mfma_f32_16x16x32_bf16 v[92:95], v[146:149], v[178:181], v[92:95]
	v_mfma_f32_16x16x32_bf16 v[88:91], v[154:157], v[178:181], v[88:91]
	v_mfma_f32_16x16x32_bf16 v[84:87], v[146:149], v[186:189], v[84:87]
	v_mfma_f32_16x16x32_bf16 v[80:83], v[154:157], v[186:189], v[80:83]
	v_mfma_f32_16x16x32_bf16 v[76:79], v[146:149], v[202:205], v[76:79]
	v_mfma_f32_16x16x32_bf16 v[72:75], v[154:157], v[202:205], v[72:75]
	v_mfma_f32_16x16x32_bf16 v[12:15], v[146:149], v[230:233], v[12:15]
	v_mfma_f32_16x16x32_bf16 v[8:11], v[154:157], v[230:233], v[8:11]
	v_mfma_f32_16x16x32_bf16 v[36:39], v[158:161], v[174:177], v[36:39]
	v_mfma_f32_16x16x32_bf16 v[32:35], v[166:169], v[174:177], v[32:35]
	v_mfma_f32_16x16x32_bf16 v[28:31], v[158:161], v[182:185], v[28:31]
	v_mfma_f32_16x16x32_bf16 v[24:27], v[166:169], v[182:185], v[24:27]
	v_mfma_f32_16x16x32_bf16 v[20:23], v[158:161], v[190:193], v[20:23]
	v_mfma_f32_16x16x32_bf16 v[16:19], v[166:169], v[190:193], v[16:19]
	v_mfma_f32_16x16x32_bf16 v[4:7], v[158:161], v[206:209], v[4:7]
	v_mfma_f32_16x16x32_bf16 v[0:3], v[166:169], v[206:209], v[0:3]
	v_mfma_f32_16x16x32_bf16 v[36:39], v[162:165], v[178:181], v[36:39]
	v_mfma_f32_16x16x32_bf16 v[32:35], v[170:173], v[178:181], v[32:35]
	v_mfma_f32_16x16x32_bf16 v[28:31], v[162:165], v[186:189], v[28:31]
	v_mfma_f32_16x16x32_bf16 v[24:27], v[170:173], v[186:189], v[24:27]
	v_mfma_f32_16x16x32_bf16 v[20:23], v[162:165], v[202:205], v[20:23]
	v_mfma_f32_16x16x32_bf16 v[16:19], v[170:173], v[202:205], v[16:19]
	v_mfma_f32_16x16x32_bf16 v[4:7], v[162:165], v[230:233], v[4:7]
	v_mfma_f32_16x16x32_bf16 v[0:3], v[170:173], v[230:233], v[0:3]
	s_barrier
	v_or_b32_e32 v142, 0x18000, v141
	v_add_u32_e32 v146, 0x18400, v141
	v_add_u32_e32 v150, 0x18800, v141
	v_add_u32_e32 v154, 0x18c00, v141
	v_or_b32_e32 v158, 0x1c000, v141
	v_add_u32_e32 v162, 0x1c400, v141
	v_add_u32_e32 v166, 0x1c800, v141
	v_add_u32_e32 v170, 0x1cc00, v141
	ds_read_b128 v[142:145], v142
	ds_read_b128 v[146:149], v146
	ds_read_b128 v[150:153], v150
	ds_read_b128 v[154:157], v154
	ds_read_b128 v[158:161], v158
	ds_read_b128 v[162:165], v162
	ds_read_b128 v[166:169], v166
	ds_read_b128 v[170:173], v170
	s_add_u32 s62, s62, s42
	s_addc_u32 s63, s63, s43
	s_mov_b32 m0, s22
	ds_read_b128 v[174:177], v140 offset:32768
	ds_read_b128 v[178:181], v140 offset:33792
	ds_read_b128 v[182:185], v140 offset:34816
	ds_read_b128 v[186:189], v140 offset:35840
	ds_read_b128 v[190:193], v140 offset:36864
	ds_read_b128 v[202:205], v140 offset:37888
	ds_read_b128 v[206:209], v140 offset:38912
	ds_read_b128 v[230:233], v140 offset:39936
	global_load_lds_dwordx4 v134, s[62:63]
	s_mov_b32 m0, s23
	s_nop 0
	global_load_lds_dwordx4 v132, s[62:63]
	s_waitcnt vmcnt(8)
	s_waitcnt lgkmcnt(0)
	s_barrier
	s_waitcnt lgkmcnt(0)
	v_mfma_f32_16x16x32_bf16 v[126:129], v[142:145], v[174:177], v[126:129]
	v_mfma_f32_16x16x32_bf16 v[122:125], v[150:153], v[174:177], v[122:125]
	v_mfma_f32_16x16x32_bf16 v[118:121], v[142:145], v[182:185], v[118:121]
	v_mfma_f32_16x16x32_bf16 v[114:117], v[150:153], v[182:185], v[114:117]
	v_mfma_f32_16x16x32_bf16 v[110:113], v[142:145], v[190:193], v[110:113]
	v_mfma_f32_16x16x32_bf16 v[106:109], v[150:153], v[190:193], v[106:109]
	v_mfma_f32_16x16x32_bf16 v[102:105], v[142:145], v[206:209], v[102:105]
	v_mfma_f32_16x16x32_bf16 v[98:101], v[150:153], v[206:209], v[98:101]
	v_mfma_f32_16x16x32_bf16 v[126:129], v[146:149], v[178:181], v[126:129]
	v_mfma_f32_16x16x32_bf16 v[122:125], v[154:157], v[178:181], v[122:125]
	v_mfma_f32_16x16x32_bf16 v[118:121], v[146:149], v[186:189], v[118:121]
	v_mfma_f32_16x16x32_bf16 v[114:117], v[154:157], v[186:189], v[114:117]
	v_mfma_f32_16x16x32_bf16 v[110:113], v[146:149], v[202:205], v[110:113]
	v_mfma_f32_16x16x32_bf16 v[106:109], v[154:157], v[202:205], v[106:109]
	v_mfma_f32_16x16x32_bf16 v[102:105], v[146:149], v[230:233], v[102:105]
	v_mfma_f32_16x16x32_bf16 v[98:101], v[154:157], v[230:233], v[98:101]
	v_mfma_f32_16x16x32_bf16 v[68:71], v[158:161], v[174:177], v[68:71]
	v_mfma_f32_16x16x32_bf16 v[64:67], v[166:169], v[174:177], v[64:67]
	v_mfma_f32_16x16x32_bf16 v[60:63], v[158:161], v[182:185], v[60:63]
	v_mfma_f32_16x16x32_bf16 v[56:59], v[166:169], v[182:185], v[56:59]
	v_mfma_f32_16x16x32_bf16 v[52:55], v[158:161], v[190:193], v[52:55]
	v_mfma_f32_16x16x32_bf16 v[48:51], v[166:169], v[190:193], v[48:51]
	v_mfma_f32_16x16x32_bf16 v[44:47], v[158:161], v[206:209], v[44:47]
	v_mfma_f32_16x16x32_bf16 v[40:43], v[166:169], v[206:209], v[40:43]
	v_mfma_f32_16x16x32_bf16 v[68:71], v[162:165], v[178:181], v[68:71]
	v_mfma_f32_16x16x32_bf16 v[64:67], v[170:173], v[178:181], v[64:67]
	v_mfma_f32_16x16x32_bf16 v[60:63], v[162:165], v[186:189], v[60:63]
	v_mfma_f32_16x16x32_bf16 v[56:59], v[170:173], v[186:189], v[56:59]
	v_mfma_f32_16x16x32_bf16 v[52:55], v[162:165], v[202:205], v[52:55]
	v_mfma_f32_16x16x32_bf16 v[48:51], v[170:173], v[202:205], v[48:51]
	v_mfma_f32_16x16x32_bf16 v[44:47], v[162:165], v[230:233], v[44:47]
	v_mfma_f32_16x16x32_bf16 v[40:43], v[170:173], v[230:233], v[40:43]
	s_barrier
; #define PG8_STAGE(bufoff, gbase, voff) do { _Pragma("unroll") for (int _i = 0; _i < 2; ++_i) \
;         __builtin_amdgcn_global_load_lds((const unsigned*)((const char*)(gbase) + (voff)[_i]), (PG8_LAS unsigned*)(lds + (bufoff) + ldsw + _i * 8192), 16, 0, 0); } while (0)
; #define PG8_LDA(dst, b, h) do { _Pragma("unroll") for (int m = 0; m < 4; ++m) _Pragma("unroll") for (int k = 0; k < 2; ++k) dst[m][k] = *(const PG8_LAS bf16x8*)(lds + PG8_SA(b, h) + aoff + m * 2048 + k * 1024); } while (0)
; #define PG8_MMA(ai, bj, At, Bt) do { __builtin_amdgcn_s_setprio(1); _Pragma("unroll") for (int m = 0; m < 4; ++m) _Pragma("unroll") for (int n = 0; n < 2; ++n) _Pragma("unroll") for (int k = 0; k < 2; ++k) \
;         acc[ai][bj][m][n] = __builtin_amdgcn_mfma_f32_16x16x32_bf16(Bt[n][k], At[m][k], acc[ai][bj][m][n], 0, 0, 0); __builtin_amdgcn_s_setprio(0); } while (0)
; #define PG8_WAIT_V(n) asm volatile("s_waitcnt vmcnt(" #n ")" ::: "memory")
; #define PG8_WAIT_L(n) asm volatile("s_waitcnt lgkmcnt(" #n ")" ::: "memory")
; #define PG8_BAR __builtin_amdgcn_s_barrier()
; #define PG8_SCHED __builtin_amdgcn_sched_barrier(0)
; template <class Epi, class Sched, bool ALIGN_EPI = false, bool SP2 = false>
; __device__ __forceinline__ void gemm_phase(PG8_LAS unsigned char* lds, const Gemm g, const Sched& S, const Epi& E) {
;     ...
;         for (int t = 0; t < nt; t += 2) {
;     ...
;             PG8_LDA(At, 1, 1); PG8_STAGE(PG8_SB(1, 0), b3, voffB); PG8_STAGE(PG8_SB(1, 1), b3 + hstep, voffB); PG8_STAGE(PG8_SA(1, 0), a3, voffA);
;             PG8_WAIT_V(8); PG8_WAIT_L(0); PG8_BAR; PG8_MMA(1, 0, At, B0); PG8_MMA(1, 1, At, B1); PG8_BAR; PG8_SCHED;
	s_mov_b32 m0, s31
	ds_read_b128 v[174:177], v140 offset:49152
	ds_read_b128 v[178:181], v140 offset:50176
	ds_read_b128 v[182:185], v140 offset:51200
	ds_read_b128 v[186:189], v140 offset:52224
	ds_read_b128 v[190:193], v140 offset:53248
	ds_read_b128 v[202:205], v140 offset:54272
	ds_read_b128 v[206:209], v140 offset:55296
	ds_read_b128 v[230:233], v140 offset:56320
	global_load_lds_dwordx4 v96, s[98:99]
	s_mov_b32 m0, s34
	s_nop 0
	global_load_lds_dwordx4 v130, s[98:99]
	s_mov_b32 m0, s65
	s_nop 0
	global_load_lds_dwordx4 v96, s[100:101]
	s_mov_b32 m0, s66
	s_nop 0
	global_load_lds_dwordx4 v130, s[100:101]
	s_sub_u32 s98, s62, s42
	s_subb_u32 s99, s63, s43
	s_add_u32 s98, s98, s8
	s_addc_u32 s99, s99, s9
	s_mov_b32 m0, s36
	s_nop 0
	global_load_lds_dwordx4 v134, s[98:99]
	s_mov_b32 m0, s64
	s_nop 0
	global_load_lds_dwordx4 v132, s[98:99]
	s_waitcnt vmcnt(8)
	s_waitcnt lgkmcnt(0)
	s_barrier
	s_waitcnt lgkmcnt(0)
	v_mfma_f32_16x16x32_bf16 v[92:95], v[142:145], v[174:177], v[92:95]
	v_mfma_f32_16x16x32_bf16 v[88:91], v[150:153], v[174:177], v[88:91]
	v_mfma_f32_16x16x32_bf16 v[84:87], v[142:145], v[182:185], v[84:87]
	v_mfma_f32_16x16x32_bf16 v[80:83], v[150:153], v[182:185], v[80:83]
	v_mfma_f32_16x16x32_bf16 v[76:79], v[142:145], v[190:193], v[76:79]
	v_mfma_f32_16x16x32_bf16 v[72:75], v[150:153], v[190:193], v[72:75]
	v_mfma_f32_16x16x32_bf16 v[12:15], v[142:145], v[206:209], v[12:15]
	v_mfma_f32_16x16x32_bf16 v[8:11], v[150:153], v[206:209], v[8:11]
	v_mfma_f32_16x16x32_bf16 v[92:95], v[146:149], v[178:181], v[92:95]
	v_mfma_f32_16x16x32_bf16 v[88:91], v[154:157], v[178:181], v[88:91]
	v_mfma_f32_16x16x32_bf16 v[84:87], v[146:149], v[186:189], v[84:87]
	v_mfma_f32_16x16x32_bf16 v[80:83], v[154:157], v[186:189], v[80:83]
	v_mfma_f32_16x16x32_bf16 v[76:79], v[146:149], v[202:205], v[76:79]
	v_mfma_f32_16x16x32_bf16 v[72:75], v[154:157], v[202:205], v[72:75]
	v_mfma_f32_16x16x32_bf16 v[12:15], v[146:149], v[230:233], v[12:15]
	v_mfma_f32_16x16x32_bf16 v[8:11], v[154:157], v[230:233], v[8:11]
	v_mfma_f32_16x16x32_bf16 v[36:39], v[158:161], v[174:177], v[36:39]
	v_mfma_f32_16x16x32_bf16 v[32:35], v[166:169], v[174:177], v[32:35]
	v_mfma_f32_16x16x32_bf16 v[28:31], v[158:161], v[182:185], v[28:31]
	v_mfma_f32_16x16x32_bf16 v[24:27], v[166:169], v[182:185], v[24:27]
	v_mfma_f32_16x16x32_bf16 v[20:23], v[158:161], v[190:193], v[20:23]
	v_mfma_f32_16x16x32_bf16 v[16:19], v[166:169], v[190:193], v[16:19]
	v_mfma_f32_16x16x32_bf16 v[4:7], v[158:161], v[206:209], v[4:7]
	v_mfma_f32_16x16x32_bf16 v[0:3], v[166:169], v[206:209], v[0:3]
	v_mfma_f32_16x16x32_bf16 v[36:39], v[162:165], v[178:181], v[36:39]
	v_mfma_f32_16x16x32_bf16 v[32:35], v[170:173], v[178:181], v[32:35]
	v_mfma_f32_16x16x32_bf16 v[28:31], v[162:165], v[186:189], v[28:31]
	v_mfma_f32_16x16x32_bf16 v[24:27], v[170:173], v[186:189], v[24:27]
	v_mfma_f32_16x16x32_bf16 v[20:23], v[162:165], v[202:205], v[20:23]
	v_mfma_f32_16x16x32_bf16 v[16:19], v[170:173], v[202:205], v[16:19]
	v_mfma_f32_16x16x32_bf16 v[4:7], v[162:165], v[230:233], v[4:7]
	v_mfma_f32_16x16x32_bf16 v[0:3], v[170:173], v[230:233], v[0:3]
	s_barrier
	s_add_u32 s60, s60, 0x100
	s_addc_u32 s61, s61, 0
	s_add_u32 s55, s55, 0x100
	s_addc_u32 s73, s73, 0
	s_cmp_ge_i32 s74, s67
	s_mov_b32 s62, s74
	s_cbranch_scc0 .LBB0_399
	s_setprio 0
	s_and_b64 vcc, exec, s[50:51]
	s_cbranch_vccz .LBB0_410
